# attention: redundant early vmcnt(0) before the tail exps removed (exps overlap the K/V DMA tail)
# speedup vs baseline: 1.0013x; 1.0013x over previous
; #define SBAR() __builtin_amdgcn_sched_barrier(0)
; #define WAIT_BAR() do { asm volatile("s_waitcnt vmcnt(0)" ::: "memory"); __syncthreads(); } while (0)
; #define RESC(a) do { if (__any((a) < 1.f)) { if (hi == 0) al_l[r32] = (a); asm volatile("s_waitcnt lgkmcnt(0)" ::: "memory"); \
;     _Pragma("unroll") for (int d = 0; d < 4; ++d) _Pragma("unroll") for (int r = 0; r < 16; ++r) o[d][r] *= al_l[crow(r, hi)]; } } while (0)
; #define ROT() do { const int t_ = s_prev; s_prev = s_cur; s_cur = s_next; s_next = t_; } while (0)
; template <bool FIRST, bool MLA>
; __device__ __forceinline__ void partialSM(f32x16& p0, f32x16& p1, f32x16& negm, float& m_reg, float& alpha) {
;     ...
;   for (int r = 0; r < 16; ++r) p0[r] = __builtin_amdgcn_exp2f(p0[r]);
; template <bool MLA> ...
;     ...
;     RESC(alB); WAIT_BAR(); ROT();
;     SBAR(); DMA_TILE(j + 2, s_next); SBAR();
;     qkt<MLA>(pA0, pA1, K_lds + s_cur * SHM_K, KR_lds + s_cur * SHM_KR, qr, qrl, negm, r32, hi);
;     finishSM(pB0, pB1, alB, l_reg, pa0, pa1, pa2, pa3);
;     pv_d0(o, vb0 + s_prev * SHM_V, pa0, pa1, pa2, pa3); partialSM<false, false>(pA0, pA1, negm, m_reg, alA);
;     RESC(alA); WAIT_BAR(); ROT();
.LBB0_106:
	v_exp_f32_e32 v218, v114
	v_exp_f32_e32 v219, v115
	v_exp_f32_e32 v220, v116
	v_exp_f32_e32 v221, v117
	v_exp_f32_e32 v222, v118
	v_exp_f32_e32 v223, v119
	v_exp_f32_e32 v224, v120
	v_exp_f32_e32 v225, v121
	v_exp_f32_e32 v226, v122
	v_exp_f32_e32 v227, v123
	v_exp_f32_e32 v228, v124
	v_exp_f32_e32 v229, v125
	v_exp_f32_e32 v234, v126
	v_exp_f32_e32 v235, v127
	v_exp_f32_e32 v236, v128
	v_exp_f32_e32 v237, v129
	s_waitcnt vmcnt(0)
	s_barrier
	s_add_i32 s31, s19, s31
	v_add_u32_e32 v82, s27, v210
	ds_read_b128 v[176:179], v82 offset:57344
	ds_read_b128 v[82:85], v82 offset:49152
	v_add_u32_e32 v180, s27, v209
	s_add_i32 s2, s30, 0
	s_add_i32 s2, s2, 0x18000
	s_add_u32 vcc_lo, s28, s48
	s_addc_u32 vcc_hi, s29, s49
	s_add_i32 m0, s31, 0xc000
	v_lshl_add_u64 v[250:251], v[172:173], 0, vcc
	global_load_lds_dwordx4 v[250:251], off
	v_exp_f32_e32 v238, v100
	v_add_f32_e32 v255, 0, v218
	v_add_f32_e32 v255, v219, v255
	s_waitcnt lgkmcnt(0)
	v_mfma_f32_32x32x16_bf16 v[114:129], v[82:85], v[158:161], v[66:81]
	v_exp_f32_e32 v239, v101
	v_add_f32_e32 v255, v220, v255
	v_add_f32_e32 v255, v221, v255
	v_mfma_f32_32x32x16_bf16 v[82:97], v[176:179], v[158:161], v[66:81]
	ds_read_b128 v[176:179], v180 offset:57344
	ds_read_b128 v[180:183], v180 offset:49152
	s_add_u32 vcc_lo, s28, 0x43c0100
	s_addc_u32 vcc_hi, s29, 0
	s_mov_b32 m0, s31
	v_lshl_add_u64 v[250:251], v[170:171], 0, vcc
	global_load_lds_dwordx4 v[250:251], off
	v_exp_f32_e32 v246, v102
	v_add_f32_e32 v255, v222, v255
	v_add_f32_e32 v255, v223, v255
	s_waitcnt lgkmcnt(0)
	v_mfma_f32_32x32x16_bf16 v[114:129], v[180:183], v[154:157], v[114:129]
	v_exp_f32_e32 v247, v103
	v_add_f32_e32 v255, v224, v255
	v_add_f32_e32 v255, v225, v255
	v_add_u32_e32 v180, s27, v208
	v_mfma_f32_32x32x16_bf16 v[82:97], v[176:179], v[154:157], v[82:97]
	ds_read_b128 v[176:179], v180 offset:57344
	ds_read_b128 v[180:183], v180 offset:49152
	s_add_u32 vcc_lo, s28, s48
	s_addc_u32 vcc_hi, s29, s49
	s_add_i32 m0, s31, 0xc400
	v_lshl_add_u64 v[250:251], v[174:175], 0, vcc
	global_load_lds_dwordx4 v[250:251], off
	v_exp_f32_e32 v249, v104
	v_add_f32_e32 v255, v226, v255
	v_add_f32_e32 v255, v227, v255
	s_waitcnt lgkmcnt(0)
	v_mfma_f32_32x32x16_bf16 v[114:129], v[180:183], v[150:153], v[114:129]
	v_exp_f32_e32 v252, v105
	v_add_f32_e32 v255, v228, v255
	v_add_f32_e32 v255, v229, v255
	v_add_u32_e32 v180, s27, v207
	v_mfma_f32_32x32x16_bf16 v[82:97], v[176:179], v[150:153], v[82:97]
	ds_read_b128 v[176:179], v180 offset:57344
	ds_read_b128 v[180:183], v180 offset:49152
	s_add_u32 vcc_lo, s28, 0x43c0180
	s_addc_u32 vcc_hi, s29, 0
	s_add_i32 m0, s31, 0x400
	v_lshl_add_u64 v[250:251], v[170:171], 0, vcc
	global_load_lds_dwordx4 v[250:251], off
	v_exp_f32_e32 v253, v106
	v_add_f32_e32 v255, v234, v255
	v_add_f32_e32 v255, v235, v255
	s_waitcnt lgkmcnt(0)
	v_mfma_f32_32x32x16_bf16 v[114:129], v[180:183], v[146:149], v[114:129]
	v_exp_f32_e32 v254, v107
	v_add_f32_e32 v255, v236, v255
	v_add_f32_e32 v255, v237, v255
	v_add_u32_e32 v180, s27, v206
	v_mfma_f32_32x32x16_bf16 v[82:97], v[176:179], v[146:149], v[82:97]
	ds_read_b128 v[176:179], v180 offset:57344
	ds_read_b128 v[180:183], v180 offset:49152
	s_lshl_b32 s32, s24, 13
	s_add_u32 vcc_lo, s28, 0x2e360600
	s_addc_u32 vcc_hi, s29, 0
	s_add_i32 m0, s23, s32
	v_lshl_add_u64 v[250:251], v[168:169], 0, vcc
	global_load_lds_dwordx4 v[250:251], off
	v_cvt_pk_bf16_f32 v100, v218, v219
	v_exp_f32_e32 v98, v98
	s_waitcnt lgkmcnt(0)
	v_mfma_f32_32x32x16_bf16 v[114:129], v[180:183], v[142:145], v[114:129]
	v_cvt_pk_bf16_f32 v101, v220, v221
	v_exp_f32_e32 v99, v99
	v_add_u32_e32 v180, s27, v205
	v_mfma_f32_32x32x16_bf16 v[82:97], v[176:179], v[142:145], v[82:97]
	ds_read_b128 v[176:179], v180 offset:57344
	ds_read_b128 v[180:183], v180 offset:49152
	v_cvt_pk_bf16_f32 v102, v222, v223
	v_exp_f32_e32 v108, v108
	s_waitcnt lgkmcnt(0)
	v_mfma_f32_32x32x16_bf16 v[114:129], v[180:183], v[138:141], v[114:129]
	v_cvt_pk_bf16_f32 v103, v224, v225
	v_exp_f32_e32 v109, v109
	v_add_u32_e32 v180, s27, v204
	v_mfma_f32_32x32x16_bf16 v[82:97], v[176:179], v[138:141], v[82:97]
	ds_read_b128 v[176:179], v180 offset:57344
	ds_read_b128 v[180:183], v180 offset:49152
	v_cvt_pk_bf16_f32 v104, v226, v227
	v_exp_f32_e32 v110, v110
	s_waitcnt lgkmcnt(0)
	v_mfma_f32_32x32x16_bf16 v[114:129], v[180:183], v[134:137], v[114:129]
	v_cvt_pk_bf16_f32 v105, v228, v229
	v_exp_f32_e32 v111, v111
	v_add_u32_e32 v180, s27, v203
	v_mfma_f32_32x32x16_bf16 v[82:97], v[176:179], v[134:137], v[82:97]
	ds_read_b128 v[176:179], v180 offset:57344
	ds_read_b128 v[180:183], v180 offset:49152
	v_cvt_pk_bf16_f32 v106, v234, v235
	v_exp_f32_e32 v112, v112
	s_waitcnt lgkmcnt(0)
	v_mfma_f32_32x32x16_bf16 v[114:129], v[180:183], v[130:133], v[114:129]
	v_cvt_pk_bf16_f32 v107, v236, v237
	v_exp_f32_e32 v113, v113
	v_add_u32_e32 v180, s2, v200
	v_mfma_f32_32x32x16_bf16 v[82:97], v[176:179], v[130:133], v[82:97]
	ds_read_b128 v[176:179], v180
	ds_read_b128 v[180:183], v180 offset:4096
	ds_read_b128 v[214:217], v198
	v_add_f32_e32 v255, v98, v255
	v_add_f32_e32 v255, v99, v255
	s_waitcnt lgkmcnt(0)
	v_mfma_f32_32x32x16_bf16 v[114:129], v[176:179], v[214:217], v[114:129]
	v_add_f32_e32 v255, v238, v255
	v_add_f32_e32 v255, v239, v255
	v_mfma_f32_32x32x16_bf16 v[82:97], v[180:183], v[214:217], v[82:97]
	v_add_u32_e32 v180, s2, v201
	ds_read_b128 v[176:179], v180
	ds_read_b128 v[180:183], v180 offset:4096
	ds_read_b128 v[214:217], v198 offset:1024
	v_add_f32_e32 v255, v246, v255
	v_add_f32_e32 v255, v247, v255
	s_waitcnt lgkmcnt(0)
; #define SBAR() __builtin_amdgcn_sched_barrier(0)
; __device__ __forceinline__ void finishSM(f32x16& p0, f32x16& p1, float alpha, float& l_reg, bf16x8& pa0, bf16x8& pa1, bf16x8& pa2, bf16x8& pa3) {
; #pragma unroll
;   for (int r = 0; r < 16; ++r) p1[r] = __builtin_amdgcn_exp2f(p1[r]);
;   float ps = 0;
; #pragma unroll
;   for (int r = 0; r < 16; ++r) ps += p0[r];
; #pragma unroll
;   for (int r = 0; r < 16; ++r) ps += p1[r];
;   { auto rr = __builtin_amdgcn_permlane32_swap(__float_as_uint(ps), __float_as_uint(ps), false, false);
;     ps = __uint_as_float(rr[0]) + __uint_as_float(rr[1]); }
;   l_reg = l_reg * alpha + ps;
;     ...
;   PK4(p0, 0, pa0); PK4(p0, 8, pa1); PK4(p1, 0, pa2); PK4(p1, 8, pa3);
; template <int D0> __device__ __forceinline__ void pv_one(f32x16& od, int vb, bf16x8 pa0, bf16x8 pa1, bf16x8 pa2, bf16x8 pa3) {
;   const s16x4 l0 = tr_read<v_rd_off(D0, 0, 0)>(vb), h0 = tr_read<v_rd_off(D0, 0, 1)>(vb), l1 = tr_read<v_rd_off(D0, 1, 0)>(vb), h1 = tr_read<v_rd_off(D0, 1, 1)>(vb);
;   const s16x4 l2 = tr_read<v_rd_off(D0, 2, 0)>(vb), h2 = tr_read<v_rd_off(D0, 2, 1)>(vb), l3 = tr_read<v_rd_off(D0, 3, 0)>(vb), h3 = tr_read<v_rd_off(D0, 3, 1)>(vb);
;   asm volatile("s_waitcnt lgkmcnt(0)" ::: "memory"); SBAR();
;     ...
;   od = __builtin_amdgcn_mfma_f32_32x32x16_bf16(pa0, PK(l0, h0), od, 0, 0, 0);
;   od = __builtin_amdgcn_mfma_f32_32x32x16_bf16(pa1, PK(l1, h1), od, 0, 0, 0);
;   od = __builtin_amdgcn_mfma_f32_32x32x16_bf16(pa2, PK(l2, h2), od, 0, 0, 0);
;   od = __builtin_amdgcn_mfma_f32_32x32x16_bf16(pa3, PK(l3, h3), od, 0, 0, 0);
;     ...
; }
; __device__ __forceinline__ void pv_d0(f32x16* o, int vb, bf16x8 pa0, bf16x8 pa1, bf16x8 pa2, bf16x8 pa3) {
;   pv_one<0>(o[0], vb, pa0, pa1, pa2, pa3); pv_one<1>(o[1], vb, pa0, pa1, pa2, pa3); pv_one<2>(o[2], vb, pa0, pa1, pa2, pa3); pv_one<3>(o[3], vb, pa0, pa1, pa2, pa3);
	v_mfma_f32_32x32x16_bf16 v[114:129], v[176:179], v[214:217], v[114:129]
	v_add_f32_e32 v255, v249, v255
	v_add_f32_e32 v255, v252, v255
	v_mfma_f32_32x32x16_bf16 v[82:97], v[180:183], v[214:217], v[82:97]
	v_add_u32_e32 v180, s2, v199
	ds_read_b128 v[176:179], v180
	ds_read_b128 v[180:183], v180 offset:4096
	ds_read_b128 v[214:217], v198 offset:2048
	v_add_f32_e32 v255, v253, v255
	v_add_f32_e32 v255, v254, v255
	s_waitcnt lgkmcnt(0)
	v_mfma_f32_32x32x16_bf16 v[114:129], v[176:179], v[214:217], v[114:129]
	v_add_f32_e32 v255, v108, v255
	v_add_f32_e32 v255, v109, v255
	v_mfma_f32_32x32x16_bf16 v[82:97], v[180:183], v[214:217], v[82:97]
	v_add_u32_e32 v180, s2, v202
	ds_read_b128 v[176:179], v180
	ds_read_b128 v[180:183], v180 offset:4096
	ds_read_b128 v[214:217], v198 offset:3072
	v_add_f32_e32 v255, v110, v255
	v_add_f32_e32 v255, v111, v255
	s_waitcnt lgkmcnt(0)
	v_mfma_f32_32x32x16_bf16 v[114:129], v[176:179], v[214:217], v[114:129]
	v_add_f32_e32 v255, v112, v255
	v_add_f32_e32 v255, v113, v255
	v_mfma_f32_32x32x16_bf16 v[82:97], v[180:183], v[214:217], v[82:97]
	v_cvt_pk_bf16_f32 v176, v253, v254
	v_cvt_pk_bf16_f32 v177, v108, v109
	v_cvt_pk_bf16_f32 v178, v110, v111
	v_cvt_pk_bf16_f32 v179, v112, v113
	v_cvt_pk_bf16_f32 v108, v98, v99
	v_cvt_pk_bf16_f32 v109, v238, v239
	v_cvt_pk_bf16_f32 v110, v246, v247
	v_cvt_pk_bf16_f32 v111, v249, v252
	v_mov_b32_e32 v98, v255
	v_add_u32_e32 v112, s11, v197
	ds_read_b64_tr_b16 v[180:181], v112 offset:0
	ds_read_b64_tr_b16 v[182:183], v112 offset:0x800
	ds_read_b64_tr_b16 v[214:215], v112 offset:0x1000
	ds_read_b64_tr_b16 v[216:217], v112 offset:0x1800
	ds_read_b64_tr_b16 v[218:219], v112 offset:0x2000
	ds_read_b64_tr_b16 v[220:221], v112 offset:0x2800
	ds_read_b64_tr_b16 v[222:223], v112 offset:0x3000
	ds_read_b64_tr_b16 v[224:225], v112 offset:0x3800
	s_waitcnt lgkmcnt(0)
	v_mov_b32_e32 v99, v98
	s_nop 1
	v_permlane32_swap_b32_e32 v98, v99
	v_permlane32_swap_b32_e32 v100, v102
	v_permlane32_swap_b32_e32 v176, v178
	v_permlane32_swap_b32_e32 v101, v103
	v_permlane32_swap_b32_e32 v104, v106
	v_permlane32_swap_b32_e32 v105, v107
	v_permlane32_swap_b32_e32 v108, v110
	v_permlane32_swap_b32_e32 v109, v111
	v_permlane32_swap_b32_e32 v177, v179
	v_mfma_f32_32x32x16_bf16 v[50:65], v[100:103], v[180:183], v[50:65]
	ds_read_b64_tr_b16 v[180:181], v112 offset:0x200
	ds_read_b64_tr_b16 v[182:183], v112 offset:0xa00
	v_mfma_f32_32x32x16_bf16 v[50:65], v[104:107], v[214:217], v[50:65]
	ds_read_b64_tr_b16 v[214:215], v112 offset:0x1200
	ds_read_b64_tr_b16 v[216:217], v112 offset:0x1a00
	v_mfma_f32_32x32x16_bf16 v[50:65], v[108:111], v[218:221], v[50:65]
	ds_read_b64_tr_b16 v[218:219], v112 offset:0x2200
	ds_read_b64_tr_b16 v[220:221], v112 offset:0x2a00
	v_mfma_f32_32x32x16_bf16 v[50:65], v[176:179], v[222:225], v[50:65]
	ds_read_b64_tr_b16 v[222:223], v112 offset:0x3200
	ds_read_b64_tr_b16 v[224:225], v112 offset:0x3a00
	s_waitcnt lgkmcnt(6)
	v_mfma_f32_32x32x16_bf16 v[34:49], v[100:103], v[180:183], v[34:49]
	ds_read_b64_tr_b16 v[180:181], v112 offset:0x400
	ds_read_b64_tr_b16 v[182:183], v112 offset:0xc00
	s_waitcnt lgkmcnt(6)
	v_mfma_f32_32x32x16_bf16 v[34:49], v[104:107], v[214:217], v[34:49]
	ds_read_b64_tr_b16 v[214:215], v112 offset:0x1400
	ds_read_b64_tr_b16 v[216:217], v112 offset:0x1c00
	s_waitcnt lgkmcnt(6)
	v_mfma_f32_32x32x16_bf16 v[34:49], v[108:111], v[218:221], v[34:49]
	ds_read_b64_tr_b16 v[218:219], v112 offset:0x2400
	ds_read_b64_tr_b16 v[220:221], v112 offset:0x2c00
	s_waitcnt lgkmcnt(6)
	v_mfma_f32_32x32x16_bf16 v[34:49], v[176:179], v[222:225], v[34:49]
	ds_read_b64_tr_b16 v[222:223], v112 offset:0x3400
	ds_read_b64_tr_b16 v[224:225], v112 offset:0x3c00
	s_waitcnt lgkmcnt(6)
	v_mfma_f32_32x32x16_bf16 v[18:33], v[100:103], v[180:183], v[18:33]
	ds_read_b64_tr_b16 v[180:181], v112 offset:0x600
	ds_read_b64_tr_b16 v[182:183], v112 offset:0xe00
	s_waitcnt lgkmcnt(6)
	v_mfma_f32_32x32x16_bf16 v[18:33], v[104:107], v[214:217], v[18:33]
	ds_read_b64_tr_b16 v[214:215], v112 offset:0x1600
	ds_read_b64_tr_b16 v[216:217], v112 offset:0x1e00
	s_waitcnt lgkmcnt(6)
	v_mfma_f32_32x32x16_bf16 v[18:33], v[108:111], v[218:221], v[18:33]
	ds_read_b64_tr_b16 v[218:219], v112 offset:0x2600
	ds_read_b64_tr_b16 v[220:221], v112 offset:0x2e00
	s_waitcnt lgkmcnt(6)
	v_mfma_f32_32x32x16_bf16 v[18:33], v[176:179], v[222:225], v[18:33]
	ds_read_b64_tr_b16 v[222:223], v112 offset:0x3600
	ds_read_b64_tr_b16 v[224:225], v112 offset:0x3e00
	s_waitcnt lgkmcnt(6)
	v_mfma_f32_32x32x16_bf16 v[2:17], v[100:103], v[180:183], v[2:17]
	v_max_f32_e32 v100, v115, v115
	v_max_f32_e32 v101, v114, v114
	v_max_f32_e32 v100, v101, v100
	v_max3_f32 v101, v116, v117, v83
	v_max3_f32 v100, v100, v82, v84
	v_max3_f32 v100, v100, v85, v118
	v_max3_f32 v101, v101, v120, v121
	s_waitcnt lgkmcnt(4)
	v_mfma_f32_32x32x16_bf16 v[2:17], v[104:107], v[214:217], v[2:17]
	v_max3_f32 v100, v100, v119, v86
	v_max3_f32 v101, v101, v88, v89
	v_max3_f32 v100, v100, v87, v122
	v_max3_f32 v101, v101, v124, v125
	v_max3_f32 v100, v100, v123, v90
	v_max3_f32 v101, v101, v92, v93
	v_max3_f32 v100, v100, v91, v126
	s_waitcnt lgkmcnt(2)
	v_mfma_f32_32x32x16_bf16 v[2:17], v[108:111], v[218:221], v[2:17]
	v_max3_f32 v101, v101, v128, v129
	v_max3_f32 v100, v100, v127, v94
	v_max3_f32 v101, v101, v96, v97
	v_max3_f32 v100, v100, v95, v101
	v_mov_b32_e32 v101, v100
	s_nop 1
	v_permlane32_swap_b32_e32 v100, v101
	s_waitcnt lgkmcnt(0)
	v_mfma_f32_32x32x16_bf16 v[2:17], v[176:179], v[222:225], v[2:17]
	v_max_f32_e32 v101, v101, v101
	v_max_f32_e32 v100, v100, v100
	v_max_f32_e32 v100, v100, v101
	v_cmp_lt_f32_e32 vcc, s40, v100
	v_mov_b32_e32 v176, 1.0
	s_cbranch_vccnz .LBB0_114
	v_cmp_gt_f32_e32 vcc, 1.0, v176
	s_cbranch_vccz .LBB0_111

; #define SBAR() __builtin_amdgcn_sched_barrier(0)
; #define WAIT_BAR() do { asm volatile("s_waitcnt vmcnt(0)" ::: "memory"); __syncthreads(); } while (0)
; #define RESC(a) do { if (__any((a) < 1.f)) { if (hi == 0) al_l[r32] = (a); asm volatile("s_waitcnt lgkmcnt(0)" ::: "memory"); \
;     _Pragma("unroll") for (int d = 0; d < 4; ++d) _Pragma("unroll") for (int r = 0; r < 16; ++r) o[d][r] *= al_l[crow(r, hi)]; } } while (0)
; #define ROT() do { const int t_ = s_prev; s_prev = s_cur; s_cur = s_next; s_next = t_; } while (0)
; template <bool FIRST, bool MLA>
; __device__ __forceinline__ void partialSM(f32x16& p0, f32x16& p1, f32x16& negm, float& m_reg, float& alpha) {
;     ...
;   for (int r = 0; r < 16; ++r) p0[r] = __builtin_amdgcn_exp2f(p0[r]);
; template <bool MLA> ...
;     ...
;   for (int j = 1; j + 1 < NT; j += 2) {
;     SBAR(); DMA_TILE(j + 1, s_next); SBAR();
;     qkt<MLA>(pB0, pB1, K_lds + s_cur * SHM_K, KR_lds + s_cur * SHM_KR, qr, qrl, negm, r32, hi);
;     finishSM(pA0, pA1, alA, l_reg, pa0, pa1, pa2, pa3);
;     pv_d0(o, vb0 + s_prev * SHM_V, pa0, pa1, pa2, pa3); partialSM<false, false>(pB0, pB1, negm, m_reg, alB);
;     RESC(alB); WAIT_BAR(); ROT();
;     SBAR(); DMA_TILE(j + 2, s_next); SBAR();
;     qkt<MLA>(pA0, pA1, K_lds + s_cur * SHM_K, KR_lds + s_cur * SHM_KR, qr, qrl, negm, r32, hi);
;     finishSM(pB0, pB1, alB, l_reg, pa0, pa1, pa2, pa3);
;     pv_d0(o, vb0 + s_prev * SHM_V, pa0, pa1, pa2, pa3); partialSM<false, false>(pA0, pA1, negm, m_reg, alA);
;     RESC(alA); WAIT_BAR(); ROT();
.LBB0_111:
	v_exp_f32_e32 v227, v114
	v_exp_f32_e32 v229, v115
	v_exp_f32_e32 v225, v116
	v_exp_f32_e32 v228, v117
	v_exp_f32_e32 v224, v118
	v_exp_f32_e32 v226, v119
	v_exp_f32_e32 v222, v120
	v_exp_f32_e32 v223, v121
	v_exp_f32_e32 v219, v122
	v_exp_f32_e32 v221, v123
	v_exp_f32_e32 v218, v124
	v_exp_f32_e32 v220, v125
	v_exp_f32_e32 v215, v126
	v_exp_f32_e32 v217, v127
	v_exp_f32_e32 v214, v128
	v_exp_f32_e32 v216, v129
	v_add_f32_e32 v0, v0, v212
	v_fmac_f32_e32 v0, v211, v195
	v_add_f32_e32 v195, v98, v99
	s_add_i32 s26, s26, 2
	s_mov_b64 s[2:3], 0x40000
	v_fmac_f32_e32 v195, v0, v213
	v_lshl_add_u64 v[168:169], v[168:169], 0, s[2:3]
	v_lshl_add_u64 v[170:171], v[170:171], 0, s[50:51]
	v_lshl_add_u64 v[172:173], v[172:173], 0, s[50:51]
	s_cmpk_gt_u32 s26, 0x7c
	v_lshl_add_u64 v[174:175], v[174:175], 0, s[50:51]
	s_waitcnt vmcnt(0)
	s_barrier
	s_cbranch_scc1 .LBB0_116
	s_mov_b32 s35, s25
	s_mov_b32 s25, s10
	v_mov_b32_e32 v211, v176
	s_branch .LBB0_101

; #define SBAR() __builtin_amdgcn_sched_barrier(0)
; #define WAIT_BAR() do { asm volatile("s_waitcnt vmcnt(0)" ::: "memory"); __syncthreads(); } while (0)
; #define RESC(a) do { if (__any((a) < 1.f)) { if (hi == 0) al_l[r32] = (a); asm volatile("s_waitcnt lgkmcnt(0)" ::: "memory"); \
;     _Pragma("unroll") for (int d = 0; d < 4; ++d) _Pragma("unroll") for (int r = 0; r < 16; ++r) o[d][r] *= al_l[crow(r, hi)]; } } while (0)
; #define ROT() do { const int t_ = s_prev; s_prev = s_cur; s_cur = s_next; s_next = t_; } while (0)
; __device__ __forceinline__ void finishSM(f32x16& p0, f32x16& p1, float alpha, float& l_reg, bf16x8& pa0, bf16x8& pa1, bf16x8& pa2, bf16x8& pa3) {
; #pragma unroll
;   for (int r = 0; r < 16; ++r) p1[r] = __builtin_amdgcn_exp2f(p1[r]);
;   float ps = 0;
; #pragma unroll
;   for (int r = 0; r < 16; ++r) ps += p0[r];
; #pragma unroll
;   for (int r = 0; r < 16; ++r) ps += p1[r];
;   { auto rr = __builtin_amdgcn_permlane32_swap(__float_as_uint(ps), __float_as_uint(ps), false, false);
;     ps = __uint_as_float(rr[0]) + __uint_as_float(rr[1]); }
;   l_reg = l_reg * alpha + ps;
;     ...
;   PK4(p0, 0, pa0); PK4(p0, 8, pa1); PK4(p1, 0, pa2); PK4(p1, 8, pa3);
; template <bool MLA> ...
;     ...
;     RESC(alB); WAIT_BAR(); ROT();
;     SBAR(); DMA_TILE(j + 2, s_next); SBAR();
;     qkt<MLA>(pA0, pA1, K_lds + s_cur * SHM_K, KR_lds + s_cur * SHM_KR, qr, qrl, negm, r32, hi);
;     finishSM(pB0, pB1, alB, l_reg, pa0, pa1, pa2, pa3);
;     pv_d0(o, vb0 + s_prev * SHM_V, pa0, pa1, pa2, pa3); partialSM<false, false>(pA0, pA1, negm, m_reg, alA);
;     RESC(alA); WAIT_BAR(); ROT();
.LBB0_130:
	v_exp_f32_e32 v208, v114
	v_exp_f32_e32 v209, v115
	v_exp_f32_e32 v210, v116
	v_exp_f32_e32 v211, v117
	v_exp_f32_e32 v212, v118
	v_exp_f32_e32 v213, v119
	v_exp_f32_e32 v214, v120
	v_exp_f32_e32 v215, v121
	v_exp_f32_e32 v216, v122
	v_exp_f32_e32 v217, v123
	v_exp_f32_e32 v218, v124
	v_exp_f32_e32 v219, v125
	v_exp_f32_e32 v220, v126
	v_exp_f32_e32 v221, v127
	v_exp_f32_e32 v222, v128
	v_exp_f32_e32 v223, v129
	s_waitcnt vmcnt(0)
	s_barrier
	s_add_i32 s24, s15, s24
	v_add_u32_e32 v82, s23, v199
	ds_read_b128 v[172:175], v82 offset:57344
	ds_read_b128 v[82:85], v82 offset:49152
	v_add_u32_e32 v176, s23, v198
	s_add_u32 vcc_lo, s2, s74
	s_addc_u32 vcc_hi, s3, s75
	s_add_i32 m0, s24, 0xc000
	v_lshl_add_u64 v[250:251], v[168:169], 0, vcc
	global_load_lds_dwordx4 v[250:251], off
	v_exp_f32_e32 v177, v103
	v_exp_f32_e32 v224, v108
	v_exp_f32_e32 v225, v109
	s_waitcnt lgkmcnt(0)
	v_mfma_f32_32x32x16_bf16 v[114:129], v[82:85], v[158:161], v[66:81]
	v_exp_f32_e32 v226, v110
	v_exp_f32_e32 v227, v111
	v_exp_f32_e32 v112, v112
	v_exp_f32_e32 v113, v113
	v_mfma_f32_32x32x16_bf16 v[82:97], v[172:175], v[158:161], v[66:81]
	ds_read_b128 v[172:175], v176 offset:57344
	ds_read_b128 v[204:207], v176 offset:49152
	v_add_u32_e32 v176, s23, v197
	s_add_u32 vcc_lo, s2, 0x1c421600
	s_addc_u32 vcc_hi, s3, 0
	s_mov_b32 m0, s24
	v_lshl_add_u64 v[250:251], v[0:1], 0, vcc
	global_load_lds_dwordx4 v[250:251], off
	s_waitcnt lgkmcnt(0)
	v_mfma_f32_32x32x16_bf16 v[82:97], v[172:175], v[154:157], v[82:97]
	v_mfma_f32_32x32x16_bf16 v[114:129], v[204:207], v[154:157], v[114:129]
	ds_read_b128 v[172:175], v176 offset:57344
	ds_read_b128 v[204:207], v176 offset:49152
	v_add_u32_e32 v176, s23, v196
	s_add_u32 vcc_lo, s2, s74
	s_addc_u32 vcc_hi, s3, s75
	s_add_i32 m0, s24, 0xc400
	v_lshl_add_u64 v[250:251], v[170:171], 0, vcc
	global_load_lds_dwordx4 v[250:251], off
	s_waitcnt lgkmcnt(0)
	v_mfma_f32_32x32x16_bf16 v[82:97], v[172:175], v[150:153], v[82:97]
	v_mfma_f32_32x32x16_bf16 v[114:129], v[204:207], v[150:153], v[114:129]
	ds_read_b128 v[172:175], v176 offset:57344
	ds_read_b128 v[204:207], v176 offset:49152
	v_add_u32_e32 v176, s23, v195
	s_add_u32 vcc_lo, s2, 0x1c421680
	s_addc_u32 vcc_hi, s3, 0
	s_add_i32 m0, s24, 0x400
	v_lshl_add_u64 v[250:251], v[0:1], 0, vcc
	global_load_lds_dwordx4 v[250:251], off
	s_waitcnt lgkmcnt(0)
	v_mfma_f32_32x32x16_bf16 v[82:97], v[172:175], v[146:149], v[82:97]
	v_mfma_f32_32x32x16_bf16 v[114:129], v[204:207], v[146:149], v[114:129]
	ds_read_b128 v[172:175], v176 offset:57344
	ds_read_b128 v[204:207], v176 offset:49152
	v_add_u32_e32 v176, s23, v183
	s_waitcnt lgkmcnt(0)
	v_mfma_f32_32x32x16_bf16 v[82:97], v[172:175], v[142:145], v[82:97]
	v_mfma_f32_32x32x16_bf16 v[114:129], v[204:207], v[142:145], v[114:129]
	ds_read_b128 v[172:175], v176 offset:57344
	ds_read_b128 v[204:207], v176 offset:49152
	v_add_u32_e32 v176, s23, v193
	s_waitcnt lgkmcnt(0)
	v_mfma_f32_32x32x16_bf16 v[82:97], v[172:175], v[138:141], v[82:97]
	v_mfma_f32_32x32x16_bf16 v[114:129], v[204:207], v[138:141], v[114:129]
	ds_read_b128 v[172:175], v176 offset:57344
	ds_read_b128 v[204:207], v176 offset:49152
	v_add_u32_e32 v176, s23, v194
	s_waitcnt lgkmcnt(0)
	v_mfma_f32_32x32x16_bf16 v[82:97], v[172:175], v[134:137], v[82:97]
	v_mfma_f32_32x32x16_bf16 v[114:129], v[204:207], v[134:137], v[114:129]
	ds_read_b128 v[172:175], v176 offset:57344
	ds_read_b128 v[204:207], v176 offset:49152
	v_exp_f32_e32 v176, v102
	s_waitcnt lgkmcnt(0)
	v_mfma_f32_32x32x16_bf16 v[82:97], v[172:175], v[130:133], v[82:97]
	v_exp_f32_e32 v172, v98
	v_add_f32_e32 v98, 0, v208
	v_add_f32_e32 v98, v209, v98
	v_add_f32_e32 v98, v210, v98
	v_add_f32_e32 v98, v211, v98
	v_add_f32_e32 v98, v212, v98
	v_add_f32_e32 v98, v213, v98
	v_add_f32_e32 v98, v214, v98
	v_add_f32_e32 v98, v215, v98
	v_add_f32_e32 v98, v216, v98
	v_add_f32_e32 v98, v217, v98
	v_add_f32_e32 v98, v218, v98
	v_add_f32_e32 v98, v219, v98
	v_add_f32_e32 v98, v220, v98
	v_exp_f32_e32 v173, v99
	v_add_f32_e32 v98, v221, v98
	v_exp_f32_e32 v174, v100
	v_add_f32_e32 v98, v222, v98
	v_exp_f32_e32 v175, v101
	v_add_f32_e32 v98, v223, v98
	v_add_f32_e32 v98, v172, v98
	v_add_f32_e32 v98, v173, v98
	v_mfma_f32_32x32x16_bf16 v[114:129], v[204:207], v[130:133], v[114:129]
	v_exp_f32_e32 v204, v104
	v_add_f32_e32 v98, v174, v98
	v_exp_f32_e32 v205, v105
	v_add_f32_e32 v98, v175, v98
	v_exp_f32_e32 v206, v106
	v_add_f32_e32 v98, v176, v98
	v_exp_f32_e32 v207, v107
	v_add_f32_e32 v98, v177, v98
	v_add_f32_e32 v98, v204, v98
	v_add_f32_e32 v98, v205, v98
	v_add_f32_e32 v98, v206, v98
	v_add_f32_e32 v98, v207, v98
	v_add_f32_e32 v98, v224, v98
	v_add_f32_e32 v98, v225, v98
	v_add_f32_e32 v98, v226, v98
	v_add_f32_e32 v98, v227, v98
	v_add_f32_e32 v98, v112, v98
	v_cvt_pk_bf16_f32 v100, v208, v209
	v_cvt_pk_bf16_f32 v101, v210, v211
	v_cvt_pk_bf16_f32 v102, v212, v213
	v_cvt_pk_bf16_f32 v103, v214, v215
	v_cvt_pk_bf16_f32 v104, v216, v217
	v_cvt_pk_bf16_f32 v105, v218, v219
	v_cvt_pk_bf16_f32 v106, v220, v221
	v_cvt_pk_bf16_f32 v107, v222, v223
	v_cvt_pk_bf16_f32 v108, v172, v173
	v_cvt_pk_bf16_f32 v109, v174, v175
	v_cvt_pk_bf16_f32 v110, v176, v177
	v_cvt_pk_bf16_f32 v111, v204, v205
	v_cvt_pk_bf16_f32 v172, v206, v207
	v_cvt_pk_bf16_f32 v173, v224, v225
	v_cvt_pk_bf16_f32 v174, v226, v227
	v_cvt_pk_bf16_f32 v175, v112, v113
	v_add_u32_e32 v112, s19, v182
	ds_read_b64_tr_b16 v[204:205], v112 offset:0
	ds_read_b64_tr_b16 v[206:207], v112 offset:0x800
	ds_read_b64_tr_b16 v[208:209], v112 offset:0x1000
	ds_read_b64_tr_b16 v[210:211], v112 offset:0x1800
	ds_read_b64_tr_b16 v[212:213], v112 offset:0x2000
	ds_read_b64_tr_b16 v[214:215], v112 offset:0x2800
	ds_read_b64_tr_b16 v[216:217], v112 offset:0x3000
	ds_read_b64_tr_b16 v[218:219], v112 offset:0x3800
	v_add_f32_e32 v98, v113, v98
	s_waitcnt lgkmcnt(0)
; #define SBAR() __builtin_amdgcn_sched_barrier(0)
; __device__ __forceinline__ float max3f(float a, float b, float c) { return __builtin_fmaxf(__builtin_fmaxf(a, b), c); }
; template <bool FIRST, bool MLA>
; __device__ __forceinline__ void partialSM(f32x16& p0, f32x16& p1, f32x16& negm, float& m_reg, float& alpha) {
;   float a = max3f(p0[0], p0[1], p1[0]), b = max3f(p0[2], p0[3], p1[1]); a = max3f(a, p1[2], p1[3]);
; #pragma unroll
;   for (int r = 4; r < 16; r += 4) { a = max3f(a, p0[r], p0[r + 1]); b = max3f(b, p0[r + 2], p0[r + 3]); a = max3f(a, p1[r], p1[r + 1]); b = max3f(b, p1[r + 2], p1[r + 3]); }
;   float pmax = fmaxf(a, b);
;   { auto rr = __builtin_amdgcn_permlane32_swap(__float_as_uint(pmax), __float_as_uint(pmax), false, false);
;     pmax = fmaxf(__uint_as_float(rr[0]), __uint_as_float(rr[1])); }
;   alpha = 1.f;
;   if constexpr (MLA) {
;     if (FIRST) m_reg = pmax;
;     else if (!__builtin_expect(__all(pmax - m_reg <= THR2), 1)) { const float mn = fmaxf(m_reg, pmax); alpha = __builtin_amdgcn_exp2f(m_reg - mn); m_reg = mn; }
; #pragma unroll
;     for (int r = 0; r < 16; ++r) { p0[r] -= m_reg; p1[r] -= m_reg; }
;   } else
;   if (FIRST || __builtin_expect(__any(pmax > THR2), 0)) {
; template <int D0> __device__ __forceinline__ void pv_one(f32x16& od, int vb, bf16x8 pa0, bf16x8 pa1, bf16x8 pa2, bf16x8 pa3) {
;   const s16x4 l0 = tr_read<v_rd_off(D0, 0, 0)>(vb), h0 = tr_read<v_rd_off(D0, 0, 1)>(vb), l1 = tr_read<v_rd_off(D0, 1, 0)>(vb), h1 = tr_read<v_rd_off(D0, 1, 1)>(vb);
;   const s16x4 l2 = tr_read<v_rd_off(D0, 2, 0)>(vb), h2 = tr_read<v_rd_off(D0, 2, 1)>(vb), l3 = tr_read<v_rd_off(D0, 3, 0)>(vb), h3 = tr_read<v_rd_off(D0, 3, 1)>(vb);
;   asm volatile("s_waitcnt lgkmcnt(0)" ::: "memory"); SBAR();
;     ...
;   od = __builtin_amdgcn_mfma_f32_32x32x16_bf16(pa0, PK(l0, h0), od, 0, 0, 0);
;   od = __builtin_amdgcn_mfma_f32_32x32x16_bf16(pa1, PK(l1, h1), od, 0, 0, 0);
;   od = __builtin_amdgcn_mfma_f32_32x32x16_bf16(pa2, PK(l2, h2), od, 0, 0, 0);
;   od = __builtin_amdgcn_mfma_f32_32x32x16_bf16(pa3, PK(l3, h3), od, 0, 0, 0);
;     ...
; }
; __device__ __forceinline__ void pv_d0(f32x16* o, int vb, bf16x8 pa0, bf16x8 pa1, bf16x8 pa2, bf16x8 pa3) {
;   pv_one<0>(o[0], vb, pa0, pa1, pa2, pa3); pv_one<1>(o[1], vb, pa0, pa1, pa2, pa3); pv_one<2>(o[2], vb, pa0, pa1, pa2, pa3); pv_one<3>(o[3], vb, pa0, pa1, pa2, pa3);
	v_mov_b32_e32 v99, v98
	s_nop 1
	v_permlane32_swap_b32_e32 v98, v99
	v_permlane32_swap_b32_e32 v100, v102
	v_permlane32_swap_b32_e32 v172, v174
	v_permlane32_swap_b32_e32 v101, v103
	v_permlane32_swap_b32_e32 v104, v106
	v_permlane32_swap_b32_e32 v105, v107
	v_permlane32_swap_b32_e32 v108, v110
	v_permlane32_swap_b32_e32 v109, v111
	v_permlane32_swap_b32_e32 v173, v175
	v_mfma_f32_32x32x16_bf16 v[2:17], v[100:103], v[204:207], v[2:17]
	ds_read_b64_tr_b16 v[204:205], v112 offset:0x200
	ds_read_b64_tr_b16 v[206:207], v112 offset:0xa00
	v_mfma_f32_32x32x16_bf16 v[2:17], v[104:107], v[208:211], v[2:17]
	ds_read_b64_tr_b16 v[208:209], v112 offset:0x1200
	ds_read_b64_tr_b16 v[210:211], v112 offset:0x1a00
	v_mfma_f32_32x32x16_bf16 v[2:17], v[108:111], v[212:215], v[2:17]
	ds_read_b64_tr_b16 v[212:213], v112 offset:0x2200
	ds_read_b64_tr_b16 v[214:215], v112 offset:0x2a00
	v_mfma_f32_32x32x16_bf16 v[2:17], v[172:175], v[216:219], v[2:17]
	ds_read_b64_tr_b16 v[216:217], v112 offset:0x3200
	ds_read_b64_tr_b16 v[218:219], v112 offset:0x3a00
	s_waitcnt lgkmcnt(6)
	v_mfma_f32_32x32x16_bf16 v[50:65], v[100:103], v[204:207], v[50:65]
	ds_read_b64_tr_b16 v[204:205], v112 offset:0x400
	ds_read_b64_tr_b16 v[206:207], v112 offset:0xc00
	s_waitcnt lgkmcnt(6)
	v_mfma_f32_32x32x16_bf16 v[50:65], v[104:107], v[208:211], v[50:65]
	ds_read_b64_tr_b16 v[208:209], v112 offset:0x1400
	ds_read_b64_tr_b16 v[210:211], v112 offset:0x1c00
	s_waitcnt lgkmcnt(6)
	v_mfma_f32_32x32x16_bf16 v[50:65], v[108:111], v[212:215], v[50:65]
	ds_read_b64_tr_b16 v[212:213], v112 offset:0x2400
	ds_read_b64_tr_b16 v[214:215], v112 offset:0x2c00
	s_waitcnt lgkmcnt(6)
	v_mfma_f32_32x32x16_bf16 v[50:65], v[172:175], v[216:219], v[50:65]
	ds_read_b64_tr_b16 v[216:217], v112 offset:0x3400
	ds_read_b64_tr_b16 v[218:219], v112 offset:0x3c00
	s_waitcnt lgkmcnt(6)
	v_mfma_f32_32x32x16_bf16 v[34:49], v[100:103], v[204:207], v[34:49]
	ds_read_b64_tr_b16 v[204:205], v112 offset:0x600
	ds_read_b64_tr_b16 v[206:207], v112 offset:0xe00
	s_waitcnt lgkmcnt(6)
	v_mfma_f32_32x32x16_bf16 v[34:49], v[104:107], v[208:211], v[34:49]
	ds_read_b64_tr_b16 v[208:209], v112 offset:0x1600
	ds_read_b64_tr_b16 v[210:211], v112 offset:0x1e00
	s_waitcnt lgkmcnt(6)
	v_mfma_f32_32x32x16_bf16 v[34:49], v[108:111], v[212:215], v[34:49]
	ds_read_b64_tr_b16 v[212:213], v112 offset:0x2600
	ds_read_b64_tr_b16 v[214:215], v112 offset:0x2e00
	s_waitcnt lgkmcnt(6)
	v_mfma_f32_32x32x16_bf16 v[34:49], v[172:175], v[216:219], v[34:49]
	ds_read_b64_tr_b16 v[216:217], v112 offset:0x3600
	ds_read_b64_tr_b16 v[218:219], v112 offset:0x3e00
	s_waitcnt lgkmcnt(6)
	v_mfma_f32_32x32x16_bf16 v[18:33], v[100:103], v[204:207], v[18:33]
	v_max_f32_e32 v100, v115, v115
	v_max_f32_e32 v101, v114, v114
	v_max_f32_e32 v100, v101, v100
	v_max3_f32 v101, v116, v117, v83
	v_max3_f32 v100, v100, v82, v84
	v_max3_f32 v100, v100, v85, v118
	v_max3_f32 v101, v101, v120, v121
	s_waitcnt lgkmcnt(4)
	v_mfma_f32_32x32x16_bf16 v[18:33], v[104:107], v[208:211], v[18:33]
	v_max3_f32 v100, v100, v119, v86
	v_max3_f32 v101, v101, v88, v89
	v_max3_f32 v100, v100, v87, v122
	v_max3_f32 v101, v101, v124, v125
	v_max3_f32 v100, v100, v123, v90
	v_max3_f32 v101, v101, v92, v93
	v_max3_f32 v100, v100, v91, v126
	s_waitcnt lgkmcnt(2)
	v_mfma_f32_32x32x16_bf16 v[18:33], v[108:111], v[212:215], v[18:33]
	v_max3_f32 v101, v101, v128, v129
	v_max3_f32 v100, v100, v127, v94
	v_max3_f32 v101, v101, v96, v97
	v_max3_f32 v100, v100, v95, v101
	v_mov_b32_e32 v101, v100
	s_nop 1
	v_permlane32_swap_b32_e32 v100, v101
	s_waitcnt lgkmcnt(0)
	v_mfma_f32_32x32x16_bf16 v[18:33], v[172:175], v[216:219], v[18:33]
	v_max_f32_e32 v101, v101, v101
	v_max_f32_e32 v100, v100, v100
	v_max_f32_e32 v100, v100, v101
	v_cmp_lt_f32_e32 vcc, s40, v100
	v_mov_b32_e32 v172, 1.0
	s_cbranch_vccnz .LBB0_138
	v_cmp_gt_f32_e32 vcc, 1.0, v172
	s_cbranch_vccz .LBB0_135

; #define SBAR() __builtin_amdgcn_sched_barrier(0)
; #define WAIT_BAR() do { asm volatile("s_waitcnt vmcnt(0)" ::: "memory"); __syncthreads(); } while (0)
; #define RESC(a) do { if (__any((a) < 1.f)) { if (hi == 0) al_l[r32] = (a); asm volatile("s_waitcnt lgkmcnt(0)" ::: "memory"); \
;     _Pragma("unroll") for (int d = 0; d < 4; ++d) _Pragma("unroll") for (int r = 0; r < 16; ++r) o[d][r] *= al_l[crow(r, hi)]; } } while (0)
; #define ROT() do { const int t_ = s_prev; s_prev = s_cur; s_cur = s_next; s_next = t_; } while (0)
; template <bool FIRST, bool MLA>
; __device__ __forceinline__ void partialSM(f32x16& p0, f32x16& p1, f32x16& negm, float& m_reg, float& alpha) {
;     ...
;   for (int r = 0; r < 16; ++r) p0[r] = __builtin_amdgcn_exp2f(p0[r]);
; template <bool MLA> ...
;     ...
;   for (int j = 1; j + 1 < NT; j += 2) {
;     SBAR(); DMA_TILE(j + 1, s_next); SBAR();
;     qkt<MLA>(pB0, pB1, K_lds + s_cur * SHM_K, KR_lds + s_cur * SHM_KR, qr, qrl, negm, r32, hi);
;     finishSM(pA0, pA1, alA, l_reg, pa0, pa1, pa2, pa3);
;     pv_d0(o, vb0 + s_prev * SHM_V, pa0, pa1, pa2, pa3); partialSM<false, false>(pB0, pB1, negm, m_reg, alB);
;     RESC(alB); WAIT_BAR(); ROT();
;     SBAR(); DMA_TILE(j + 2, s_next); SBAR();
;     qkt<MLA>(pA0, pA1, K_lds + s_cur * SHM_K, KR_lds + s_cur * SHM_KR, qr, qrl, negm, r32, hi);
;     finishSM(pB0, pB1, alB, l_reg, pa0, pa1, pa2, pa3);
;     pv_d0(o, vb0 + s_prev * SHM_V, pa0, pa1, pa2, pa3); partialSM<false, false>(pA0, pA1, negm, m_reg, alA);
;     RESC(alA); WAIT_BAR(); ROT();
.LBB0_135:
	v_exp_f32_e32 v217, v114
	v_exp_f32_e32 v219, v115
	v_exp_f32_e32 v215, v116
	v_exp_f32_e32 v218, v117
	v_exp_f32_e32 v214, v118
	v_exp_f32_e32 v216, v119
	v_exp_f32_e32 v212, v120
	v_exp_f32_e32 v213, v121
	v_exp_f32_e32 v209, v122
	v_exp_f32_e32 v211, v123
	v_exp_f32_e32 v208, v124
	v_exp_f32_e32 v210, v125
	v_exp_f32_e32 v205, v126
	v_exp_f32_e32 v207, v127
	v_exp_f32_e32 v204, v128
	v_exp_f32_e32 v206, v129
	s_add_i32 s18, s18, 2
	v_add_f32_e32 v100, v201, v202
	s_add_u32 s2, s2, 0xc0000
	v_fmac_f32_e32 v100, v200, v180
	v_add_f32_e32 v180, v98, v99
	s_addc_u32 s3, s3, 0
	v_fmac_f32_e32 v180, v100, v203
	s_cmpk_gt_u32 s18, 0x7c
	s_waitcnt vmcnt(0)
	s_barrier
	s_cbranch_scc1 .LBB0_139
	s_mov_b32 s23, s17
	s_mov_b32 s17, s13
	v_mov_b32_e32 v200, v172
	s_branch .LBB0_125
